# nt hint on P3's projection-row loads as well (on v73)
# baseline (speedup 1.0000x reference)
; __device__ __forceinline__ void prep_even_phase(const Ctx& F) {
;     ...
;     for (int ch = gw; ch < T / 4; ch += NGW) {
;         u32x4 rq[4], rkv[4], rc[4], rpv[4]; bf16_t kr[4][2]; int ps[4];
; #pragma unroll
;         for (int u = 0; u < 4; ++u) {
;             const int row = 4 * ch + u, s = row % S;
;             const bf16_t* p = proj + (size_t)row * IN_EVEN_P;
;             rq[u] = lane < 48 ? *(const u32x4*)(p + 8 * lane) : z4;
;             rkv[u] = *(const u32x4*)(p + 384 + 8 * l32);
;             rc[u] = *(const u32x4*)(p + RW_OFF + 1536 + 8 * l32);
;             rpv[u] = s > 0 ? *(const u32x4*)(p + RW_OFF + 1536 + 8 * l32 - IN_EVEN_P) : z4;
;             kr[u][0] = p[640 + (lane & 15)]; kr[u][1] = p[656 + (lane & 15)];
;             ps[u] = F_pos[row];
;         }
.LBB0_301:
	s_mul_i32 s16, s22, 0x1400
	s_mul_hi_i32 s17, s22, 0x1400
	s_add_u32 s16, s70, s16
	s_addc_u32 s17, s71, s17
	v_mov_b32_e32 v64, 0
	v_mov_b32_e32 v65, 0
	v_mov_b32_e32 v66, 0
	v_mov_b32_e32 v67, 0
	s_and_saveexec_b64 s[28:29], s[4:5]
	s_cbranch_execz .LBB0_303
	v_lshl_add_u64 v[8:9], v[72:73], 1, s[16:17]
	global_load_dwordx4 v[64:67], v[8:9], off nt
.LBB0_303:
	s_or_b64 exec, exec, s[28:29]
	v_lshl_add_u64 v[8:9], s[16:17], 0, v[74:75]
	v_add_co_u32_e32 v10, vcc, 0x1000, v8
	s_ashr_i32 s23, s22, 31
	s_nop 0
	v_addc_co_u32_e32 v11, vcc, 0, v9, vcc
	global_load_dwordx4 v[68:71], v74, s[16:17] offset:768 nt
	global_load_dwordx4 v[56:59], v[10:11], off offset:320 nt
	s_and_b32 s21, s22, 0x800007fc
	v_mov_b32_e32 v48, 0
	s_cmp_lt_i32 s21, 1
	v_mov_b32_e32 v60, 0
	v_mov_b32_e32 v61, 0
	v_mov_b32_e32 v62, 0
	v_mov_b32_e32 v63, 0
	s_cbranch_scc1 .LBB0_305
	v_lshl_add_u64 v[8:9], v[8:9], 0, s[24:25]
	v_add_co_u32_e32 v8, vcc, 0xfffff000, v8
	s_nop 1
	v_addc_co_u32_e32 v9, vcc, -1, v9, vcc
	global_load_dwordx4 v[60:63], v[8:9], off offset:-1024 nt
.LBB0_305:
	v_lshlrev_b32_e32 v88, 1, v76
	global_load_ushort v98, v88, s[16:17] offset:1280 nt
	global_load_ushort v97, v88, s[16:17] offset:1312 nt
	s_lshl_b64 s[16:17], s[22:23], 2
	s_add_u32 s16, s18, s16
	s_addc_u32 s17, s19, s17
	v_mov_b64_e32 v[8:9], s[16:17]
	s_waitcnt lgkmcnt(0)
	flat_load_dword v99, v[8:9]
	s_add_i32 s34, s22, 1
	s_mul_i32 s28, s34, 0x1400
	s_mul_hi_i32 s21, s34, 0x1400
	s_add_u32 s28, s70, s28
	s_addc_u32 s29, s71, s21
	v_mov_b32_e32 v49, 0
	v_mov_b32_e32 v50, 0
	v_mov_b32_e32 v51, 0
	s_and_saveexec_b64 s[30:31], s[4:5]
	s_cbranch_execz .LBB0_307
	v_lshl_add_u64 v[8:9], v[72:73], 1, s[28:29]
	global_load_dwordx4 v[48:51], v[8:9], off nt
.LBB0_307:
	s_or_b64 exec, exec, s[30:31]
	v_lshl_add_u64 v[8:9], s[28:29], 0, v[74:75]
	v_add_co_u32_e32 v10, vcc, 0x1000, v8
	s_ashr_i32 s35, s34, 31
	s_nop 0
	v_addc_co_u32_e32 v11, vcc, 0, v9, vcc
	global_load_dwordx4 v[52:55], v74, s[28:29] offset:768 nt
	global_load_dwordx4 v[40:43], v[10:11], off offset:320 nt
	s_and_b32 s21, s34, 0x800007fd
	v_mov_b32_e32 v32, 0
	s_cmp_lt_i32 s21, 1
	v_mov_b32_e32 v44, 0
	v_mov_b32_e32 v45, 0
	v_mov_b32_e32 v46, 0
	v_mov_b32_e32 v47, 0
	s_cbranch_scc1 .LBB0_309
	v_lshl_add_u64 v[8:9], v[8:9], 0, s[24:25]
	v_add_co_u32_e32 v8, vcc, 0xfffff000, v8
	s_nop 1
	v_addc_co_u32_e32 v9, vcc, -1, v9, vcc
	global_load_dwordx4 v[44:47], v[8:9], off offset:-1024 nt
.LBB0_309:
	v_mov_b64_e32 v[8:9], s[16:17]
	global_load_ushort v95, v88, s[28:29] offset:1280 nt
	global_load_ushort v94, v88, s[28:29] offset:1312 nt
	flat_load_dword v96, v[8:9] offset:4
	s_add_i32 s30, s22, 2
	s_mul_i32 s28, s30, 0x1400
	s_mul_hi_i32 s21, s30, 0x1400
	s_add_u32 s28, s70, s28
	s_addc_u32 s29, s71, s21
	v_mov_b32_e32 v33, 0
	v_mov_b32_e32 v34, 0
	v_mov_b32_e32 v35, 0
	s_and_saveexec_b64 s[36:37], s[4:5]
	s_cbranch_execz .LBB0_311
	v_lshl_add_u64 v[8:9], v[72:73], 1, s[28:29]
	global_load_dwordx4 v[32:35], v[8:9], off nt
.LBB0_311:
	s_or_b64 exec, exec, s[36:37]
	v_lshl_add_u64 v[8:9], s[28:29], 0, v[74:75]
	v_add_co_u32_e32 v10, vcc, 0x1000, v8
	s_ashr_i32 s31, s30, 31
	s_nop 0
	v_addc_co_u32_e32 v11, vcc, 0, v9, vcc
	global_load_dwordx4 v[36:39], v74, s[28:29] offset:768 nt
	global_load_dwordx4 v[24:27], v[10:11], off offset:320 nt
	s_and_b32 s21, s30, 0x800007fe
	v_mov_b32_e32 v16, 0
	s_cmp_lt_i32 s21, 1
	v_mov_b32_e32 v28, 0
	v_mov_b32_e32 v29, 0
	v_mov_b32_e32 v30, 0
	v_mov_b32_e32 v31, 0
	s_cbranch_scc1 .LBB0_313
	v_lshl_add_u64 v[8:9], v[8:9], 0, s[24:25]
	v_add_co_u32_e32 v8, vcc, 0xfffff000, v8
	s_nop 1
	v_addc_co_u32_e32 v9, vcc, -1, v9, vcc
	global_load_dwordx4 v[28:31], v[8:9], off offset:-1024 nt
.LBB0_313:
	v_mov_b64_e32 v[8:9], s[16:17]
	global_load_ushort v92, v88, s[28:29] offset:1280 nt
	global_load_ushort v91, v88, s[28:29] offset:1312 nt
	flat_load_dword v93, v[8:9] offset:8
	s_add_i32 s28, s22, 3
	s_mul_i32 s29, s28, 0x1400
	s_mul_hi_i32 s21, s28, 0x1400
	s_add_u32 s36, s70, s29
	s_addc_u32 s37, s71, s21
	v_mov_b32_e32 v17, 0
	v_mov_b32_e32 v18, 0
	v_mov_b32_e32 v19, 0
	s_and_saveexec_b64 s[38:39], s[4:5]
	s_cbranch_execz .LBB0_315
	v_lshl_add_u64 v[8:9], v[72:73], 1, s[36:37]
	global_load_dwordx4 v[16:19], v[8:9], off nt
.LBB0_315:
	s_or_b64 exec, exec, s[38:39]
	v_lshl_add_u64 v[12:13], s[36:37], 0, v[74:75]
	v_add_co_u32_e32 v8, vcc, 0x1000, v12
	s_ashr_i32 s29, s28, 31
	s_nop 0
	v_addc_co_u32_e32 v9, vcc, 0, v13, vcc
	global_load_dwordx4 v[20:23], v74, s[36:37] offset:768 nt
	s_nop 0
	global_load_dwordx4 v[8:11], v[8:9], off offset:320 nt
	s_and_b32 s21, s28, 0x800007ff
	s_cmp_lt_i32 s21, 1
	s_cbranch_scc1 .LBB0_317
	v_lshl_add_u64 v[12:13], v[12:13], 0, s[24:25]
	v_add_co_u32_e32 v12, vcc, 0xfffff000, v12
	s_nop 1
	v_addc_co_u32_e32 v13, vcc, -1, v13, vcc
	global_load_dwordx4 v[12:15], v[12:13], off offset:-1024 nt
	s_branch .LBB0_318

; __device__ __forceinline__ float wave_sum_fast(float x) { x = reduce16(x); return (rl_(x, 0) + rl_(x, 16)) + (rl_(x, 32) + rl_(x, 48)); }
; __device__ __forceinline__ void prep_even_phase(const Ctx& F) {
;     ...
;             kr[u][0] = p[640 + (lane & 15)]; kr[u][1] = p[656 + (lane & 15)];
;             ps[u] = F_pos[row];
;         }
; #pragma unroll
;         for (int u = 0; u < 4; ++u) {
;             const int row = 4 * ch + u, b = row / S, s = row % S;
;             float f[8]; float sq = 0.f, skv = 0.f;
;             unpack8(rq[u], f);
; #pragma unroll
;             for (int e = 0; e < 8; ++e) sq += f[e] * f[e];
;             unpack8(rkv[u], f);
; #pragma unroll
;             for (int e = 0; e < 8; ++e) skv += f[e] * f[e];
;             sq = wave_sum_fast(sq); skv = wave_sum_fast(skv) * 0.5f;
;             if (lane == 0) { stats[2 * row] = 1.0f / sqrtf(sq * (1.0f / 384.f) + 1e-6f); stats[2 * row + 1] = 1.0f / sqrtf(skv * (1.0f / 256.f) + 1e-6f); }
.LBB0_318:
	v_mov_b64_e32 v[100:101], s[16:17]
	global_load_ushort v89, v88, s[36:37] offset:1280 nt
	s_nop 0
	global_load_ushort v88, v88, s[36:37] offset:1312 nt
	s_waitcnt vmcnt(0)
	v_lshlrev_b32_e32 v102, 16, v66
	flat_load_dword v90, v[100:101] offset:12
	v_lshlrev_b32_e32 v100, 16, v64
	v_and_b32_e32 v64, 0xffff0000, v64
	v_mul_f32_e32 v64, v64, v64
	v_lshlrev_b32_e32 v101, 16, v65
	v_fmac_f32_e32 v64, v100, v100
	v_and_b32_e32 v65, 0xffff0000, v65
	v_fmac_f32_e32 v64, v101, v101
	v_fmac_f32_e32 v64, v65, v65
	v_and_b32_e32 v66, 0xffff0000, v66
	v_fmac_f32_e32 v64, v102, v102
	v_lshlrev_b32_e32 v103, 16, v67
	v_fmac_f32_e32 v64, v66, v66
	v_and_b32_e32 v66, 0xffff0000, v68
	v_and_b32_e32 v67, 0xffff0000, v67
	v_fmac_f32_e32 v64, v103, v103
	v_lshlrev_b32_e32 v65, 16, v68
	v_mul_f32_e32 v66, v66, v66
	v_fmac_f32_e32 v64, v67, v67
	v_lshlrev_b32_e32 v67, 16, v69
	v_fmac_f32_e32 v66, v65, v65
	v_and_b32_e32 v68, 0xffff0000, v69
	v_fmac_f32_e32 v66, v67, v67
	v_lshlrev_b32_e32 v69, 16, v70
	v_fmac_f32_e32 v66, v68, v68
	v_and_b32_e32 v70, 0xffff0000, v70
	v_fmac_f32_e32 v66, v69, v69
	v_add_f32_dpp v64, v64, v64 quad_perm:[1,0,3,2] row_mask:0xf bank_mask:0xf bound_ctrl:1
	v_lshlrev_b32_e32 v100, 16, v71
	v_fmac_f32_e32 v66, v70, v70
	v_add_f32_dpp v64, v64, v64 quad_perm:[2,3,0,1] row_mask:0xf bank_mask:0xf bound_ctrl:1
	v_and_b32_e32 v71, 0xffff0000, v71
	v_fmac_f32_e32 v66, v100, v100
	v_add_f32_dpp v64, v64, v64 row_half_mirror row_mask:0xf bank_mask:0xf bound_ctrl:1
	v_fmac_f32_e32 v66, v71, v71
	s_nop 0
	v_add_f32_dpp v64, v64, v64 row_mirror row_mask:0xf bank_mask:0xf bound_ctrl:1
	s_nop 0
	v_readlane_b32 s38, v64, 0
	v_readlane_b32 s21, v64, 16
	v_readlane_b32 s39, v64, 32
	v_readlane_b32 s42, v64, 48
	v_add_f32_dpp v64, v66, v66 quad_perm:[1,0,3,2] row_mask:0xf bank_mask:0xf bound_ctrl:1
	s_nop 1
	v_add_f32_dpp v64, v64, v64 quad_perm:[2,3,0,1] row_mask:0xf bank_mask:0xf bound_ctrl:1
	s_nop 1
	v_add_f32_dpp v64, v64, v64 row_half_mirror row_mask:0xf bank_mask:0xf bound_ctrl:1
	s_nop 1
	v_add_f32_dpp v64, v64, v64 row_mirror row_mask:0xf bank_mask:0xf bound_ctrl:1
	s_nop 0
	v_readlane_b32 s16, v64, 0
	v_readlane_b32 s56, v64, 16
	v_readlane_b32 s17, v64, 32
	v_readlane_b32 s57, v64, 48
	s_and_saveexec_b64 s[36:37], s[6:7]
	s_cbranch_execnz .LBB0_321
	s_or_b64 exec, exec, s[36:37]
	s_and_saveexec_b64 s[16:17], s[8:9]
	s_cbranch_execnz .LBB0_322
